# layer-0 input modulation no longer copies the inputs to the X buffer; layer 0's out-proj epilogue reads the residual rows from the inputs in place
# speedup vs baseline: 1.0164x; 1.0064x over previous
.LBB0_33:
	v_readlane_b32 s7, v241, 20
	v_readlane_b32 s8, v243, 5
	v_readlane_b32 s14, v243, 11
	v_add_u32_e32 v52, s7, v42
	v_add_u32_e32 v35, 0xfffff000, v52
	v_lshrrev_b32_e32 v35, 10, v35
	s_movk_i32 s7, 0xfff
	v_add_u32_e32 v35, 1, v35
	v_cmp_lt_i32_e32 vcc, s7, v52
	v_readlane_b32 s15, v243, 12
	v_readlane_b32 s9, v243, 6
	v_cndmask_b32_e32 v35, 0, v35, vcc
	v_mov_b64_e32 v[44:45], s[14:15]
	v_mad_u64_u32 v[44:45], s[8:9], v35, s33, v[44:45]
	s_mov_b64 s[8:9], 0x1000
	s_nop 0
	v_lshl_add_u64 v[46:47], v[44:45], 0, s[8:9]
	v_ashrrev_i32_e32 v53, 31, v52
	v_lshl_add_u64 v[54:55], v[44:45], 0, v[128:129]
	v_lshl_add_u64 v[48:49], v[46:47], 0, v[128:129]
	v_mov_b32_e32 v35, v129
	v_mov_b32_e32 v37, v129
	v_mov_b32_e32 v39, v129
	v_lshlrev_b64 v[44:45], 12, v[52:53]
	v_lshl_add_u64 v[56:57], v[46:47], 0, v[34:35]
	v_lshl_add_u64 v[58:59], v[46:47], 0, v[36:37]
	v_lshl_add_u64 v[60:61], v[46:47], 0, v[38:39]
	v_lshl_add_u64 v[62:63], v[32:33], 0, v[44:45]
	global_load_dwordx4 v[44:47], v[54:55], off
	s_nop 0
	global_load_dwordx4 v[48:51], v[48:49], off
	v_readlane_b32 s7, v240, 54
	s_and_b64 vcc, exec, s[4:5]
	v_readlane_b32 s10, v243, 7
	v_add_u32_e32 v42, s7, v42
	v_readlane_b32 s11, v243, 8
	v_readlane_b32 s12, v243, 9
	v_readlane_b32 s13, v243, 10
	v_readlane_b32 s16, v243, 13
	v_readlane_b32 s17, v243, 14
	v_readlane_b32 s18, v243, 15
	v_readlane_b32 s19, v243, 16
	v_readlane_b32 s20, v243, 17
	v_readlane_b32 s21, v243, 18
	v_readlane_b32 s22, v243, 19
	v_readlane_b32 s23, v243, 20
	s_waitcnt vmcnt(0)
	v_pk_add_f32 v[48:49], v[48:49], 1.0 op_sel_hi:[1,0]
	s_nop 0
	v_pk_fma_f32 v[44:45], v[28:29], v[48:49], v[44:45]
	s_nop 0
	v_cvt_pk_bf16_f32 v64, v44, v45
	v_pk_add_f32 v[44:45], v[50:51], 1.0 op_sel_hi:[1,0]
	s_nop 0
	v_pk_fma_f32 v[44:45], v[30:31], v[44:45], v[46:47]
	s_nop 0
	v_cvt_pk_bf16_f32 v65, v44, v45
	v_lshlrev_b64 v[44:45], 11, v[52:53]
	v_lshl_add_u64 v[52:53], v[40:41], 0, v[44:45]
	global_load_dwordx4 v[44:47], v[54:55], off offset:1024
	global_load_dwordx4 v[48:51], v[56:57], off
	s_waitcnt vmcnt(0)
	v_pk_add_f32 v[48:49], v[48:49], 1.0 op_sel_hi:[1,0]
	s_nop 0
	v_pk_fma_f32 v[44:45], v[24:25], v[48:49], v[44:45]
	s_nop 0
	v_cvt_pk_bf16_f32 v56, v44, v45
	v_pk_add_f32 v[44:45], v[50:51], 1.0 op_sel_hi:[1,0]
	s_nop 0
	v_pk_fma_f32 v[44:45], v[26:27], v[44:45], v[46:47]
	s_nop 0
	v_cvt_pk_bf16_f32 v57, v44, v45
	global_load_dwordx4 v[44:47], v[54:55], off offset:2048
	global_load_dwordx4 v[48:51], v[58:59], off
	s_waitcnt vmcnt(0)
	v_pk_add_f32 v[48:49], v[48:49], 1.0 op_sel_hi:[1,0]
	s_nop 0
	v_pk_fma_f32 v[44:45], v[20:21], v[48:49], v[44:45]
	s_nop 0
	v_cvt_pk_bf16_f32 v58, v44, v45
	v_pk_add_f32 v[44:45], v[50:51], 1.0 op_sel_hi:[1,0]
	s_nop 0
	v_pk_fma_f32 v[44:45], v[22:23], v[44:45], v[46:47]
	s_nop 0
	v_cvt_pk_bf16_f32 v59, v44, v45
	global_load_dwordx4 v[44:47], v[54:55], off offset:3072
	global_load_dwordx4 v[48:51], v[60:61], off
	s_nop 0
	global_store_dwordx2 v[52:53], v[64:65], off
	global_store_dwordx2 v[52:53], v[56:57], off offset:512
	global_store_dwordx2 v[52:53], v[58:59], off offset:1024
	v_mov_b64_e32 v[30:31], v[14:15]
	v_mov_b64_e32 v[26:27], v[10:11]
	v_mov_b64_e32 v[22:23], v[6:7]
	v_mov_b64_e32 v[28:29], v[12:13]
	v_mov_b64_e32 v[24:25], v[8:9]
	v_mov_b64_e32 v[20:21], v[4:5]
	s_waitcnt vmcnt(3)
	v_pk_add_f32 v[48:49], v[48:49], 1.0 op_sel_hi:[1,0]
	s_nop 0
	v_pk_fma_f32 v[44:45], v[16:17], v[48:49], v[44:45]
	v_pk_add_f32 v[16:17], v[50:51], 1.0 op_sel_hi:[1,0]
	v_cvt_pk_bf16_f32 v44, v44, v45
	v_pk_fma_f32 v[16:17], v[18:19], v[16:17], v[46:47]
	s_nop 0
	v_cvt_pk_bf16_f32 v45, v16, v17
	v_mov_b64_e32 v[18:19], v[2:3]
	v_mov_b64_e32 v[16:17], v[0:1]
	global_store_dwordx2 v[52:53], v[44:45], off offset:1536
	s_cbranch_vccnz .LBB0_37

.LBB0_128:
	s_mul_i32 s5, s10, 0x5000
	v_add_u32_e32 v156, s5, v142
	v_lshl_add_u64 v[126:127], v[124:125], 0, s[6:7]
	v_readfirstlane_b32 s5, v156
	v_add_u32_e32 v136, 0x1000, v156
	v_lshl_add_u64 v[134:135], v[126:127], 0, s[2:3]
	s_mov_b32 m0, s5
	v_lshl_add_u64 v[138:139], v[122:123], 0, s[6:7]
	v_readfirstlane_b32 s5, v136
	s_waitcnt vmcnt(5)
	s_barrier
	global_load_lds_dwordx4 v[134:135], off
	v_lshl_add_u64 v[134:135], v[138:139], 0, s[2:3]
	s_mov_b32 m0, s5
	v_add_u32_e32 v140, 0x2000, v156
	global_load_lds_dwordx4 v[134:135], off
	v_lshl_add_u64 v[134:135], v[120:121], 0, s[6:7]
	v_readfirstlane_b32 s5, v140
	v_lshl_add_u64 v[136:137], v[134:135], 0, s[2:3]
	s_mov_b32 m0, s5
	v_add_u32_e32 v154, 0x3000, v156
	global_load_lds_dwordx4 v[136:137], off
	v_lshl_add_u64 v[136:137], v[118:119], 0, s[6:7]
	v_readfirstlane_b32 s5, v154
	v_lshl_add_u64 v[140:141], v[136:137], 0, s[2:3]
	s_mov_b32 m0, s5
	v_add_u32_e32 v156, 0x4000, v156
	global_load_lds_dwordx4 v[140:141], off
	v_lshl_add_u64 v[140:141], v[116:117], 0, s[6:7]
	v_readfirstlane_b32 s5, v156
	v_lshl_add_u64 v[154:155], v[140:141], 0, s[2:3]
	s_mov_b32 m0, s5
	s_mul_i32 s5, s1, 0x5000
	global_load_lds_dwordx4 v[154:155], off
	v_or_b32_e32 v154, s5, v147
	v_add_u32_e32 v170, v154, v128
	ds_read_b128 v[154:157], v170
	ds_read_b128 v[158:161], v170 offset:1024
	ds_read_b128 v[162:165], v170 offset:2048
	ds_read_b128 v[166:169], v170 offset:3072
	ds_read_b128 v[200:203], v170 offset:4096
	ds_read_b128 v[204:207], v170 offset:5120
	v_or_b32_e32 v170, s5, v149
	v_add_u32_e32 v170, v170, v148
	s_add_i32 s1, s1, 1
	s_add_i32 s10, s10, 1
	ds_read_b128 v[208:211], v170 offset:12288
	ds_read_b128 v[212:215], v170 offset:13312
	ds_read_b128 v[216:219], v170 offset:14336
	ds_read_b128 v[220:223], v170 offset:15360
	s_cmp_lg_u32 s1, 3
	s_cselect_b32 s1, s1, 0
	s_cmp_lg_u32 s10, 3
	s_cselect_b32 s5, s10, 0
	s_mul_i32 s10, s5, 0x5000
	s_waitcnt lgkmcnt(0)
	v_mfma_f32_16x16x32_bf16 v[92:95], v[208:211], v[154:157], v[92:95]
	v_lshl_add_u64 v[126:127], v[126:127], 0, s[30:31]
	s_waitcnt vmcnt(5)
	s_barrier
	v_mfma_f32_16x16x32_bf16 v[88:91], v[212:215], v[154:157], v[88:91]
	s_add_i32 s5, s5, 1
	v_mfma_f32_16x16x32_bf16 v[84:87], v[216:219], v[154:157], v[84:87]
	v_mfma_f32_16x16x32_bf16 v[80:83], v[220:223], v[154:157], v[80:83]
	v_add_u32_e32 v154, s10, v142
	s_nop 0
	v_readfirstlane_b32 s10, v154
	s_mov_b32 m0, s10
	v_mfma_f32_16x16x32_bf16 v[76:79], v[208:211], v[158:161], v[76:79]
	global_load_lds_dwordx4 v[126:127], off
	v_lshl_add_u64 v[126:127], v[138:139], 0, s[30:31]
	v_add_u32_e32 v138, 0x1000, v154
	v_mfma_f32_16x16x32_bf16 v[72:75], v[212:215], v[158:161], v[72:75]
	v_readfirstlane_b32 s10, v138
	s_mov_b32 m0, s10
	s_nop 0
	global_load_lds_dwordx4 v[126:127], off
	v_lshl_add_u64 v[126:127], v[134:135], 0, s[30:31]
	v_add_u32_e32 v134, 0x2000, v154
	v_mfma_f32_16x16x32_bf16 v[68:71], v[216:219], v[158:161], v[68:71]
	v_readfirstlane_b32 s10, v134
	v_add_u32_e32 v134, 0x3000, v154
	s_mov_b32 m0, s10
	v_readfirstlane_b32 s10, v134
	v_add_u32_e32 v134, 0x4000, v154
	global_load_lds_dwordx4 v[126:127], off
	v_lshl_add_u64 v[126:127], v[136:137], 0, s[30:31]
	s_mov_b32 m0, s10
	v_readfirstlane_b32 s10, v134
	global_load_lds_dwordx4 v[126:127], off
	v_lshl_add_u64 v[126:127], v[140:141], 0, s[30:31]
	s_mov_b32 m0, s10
	s_mul_i32 s10, s1, 0x5000
	global_load_lds_dwordx4 v[126:127], off
	v_or_b32_e32 v126, s10, v147
	v_add_u32_e32 v126, v126, v128
	v_mfma_f32_16x16x32_bf16 v[64:67], v[220:223], v[158:161], v[64:67]
	s_add_i32 s1, s1, 1
	s_cmp_lg_u32 s1, 3
	s_cselect_b32 s1, s1, 0
	v_mfma_f32_16x16x32_bf16 v[60:63], v[208:211], v[162:165], v[60:63]
	s_cmp_lg_u32 s5, 3
	v_mfma_f32_16x16x32_bf16 v[56:59], v[212:215], v[162:165], v[56:59]
	v_mfma_f32_16x16x32_bf16 v[52:55], v[216:219], v[162:165], v[52:55]
	v_mfma_f32_16x16x32_bf16 v[48:51], v[220:223], v[162:165], v[48:51]
	v_mfma_f32_16x16x32_bf16 v[44:47], v[208:211], v[166:169], v[44:47]
	v_mfma_f32_16x16x32_bf16 v[40:43], v[212:215], v[166:169], v[40:43]
	v_mfma_f32_16x16x32_bf16 v[36:39], v[216:219], v[166:169], v[36:39]
	v_mfma_f32_16x16x32_bf16 v[32:35], v[220:223], v[166:169], v[32:35]
	ds_read_b128 v[134:137], v126
	ds_read_b128 v[138:141], v126 offset:1024
	ds_read_b128 v[154:157], v126 offset:2048
	ds_read_b128 v[158:161], v126 offset:3072
	ds_read_b128 v[162:165], v126 offset:4096
	ds_read_b128 v[166:169], v126 offset:5120
	v_or_b32_e32 v126, s10, v149
	v_add_u32_e32 v126, v126, v148
	v_mfma_f32_16x16x32_bf16 v[28:31], v[208:211], v[200:203], v[28:31]
	s_cselect_b32 s10, s5, 0
	s_add_u32 s6, s6, 0x80
	s_addc_u32 s7, s7, 0
	v_mfma_f32_16x16x32_bf16 v[24:27], v[212:215], v[200:203], v[24:27]
	s_cmpk_eq_i32 s6, 0x780
	v_mfma_f32_16x16x32_bf16 v[20:23], v[216:219], v[200:203], v[20:23]
	v_mfma_f32_16x16x32_bf16 v[16:19], v[220:223], v[200:203], v[16:19]
	v_mfma_f32_16x16x32_bf16 v[8:11], v[208:211], v[204:207], v[8:11]
	v_mfma_f32_16x16x32_bf16 v[4:7], v[212:215], v[204:207], v[4:7]
	v_mfma_f32_16x16x32_bf16 v[12:15], v[216:219], v[204:207], v[12:15]
	v_mfma_f32_16x16x32_bf16 v[0:3], v[220:223], v[204:207], v[0:3]
	ds_read_b128 v[200:203], v126 offset:12288
	ds_read_b128 v[204:207], v126 offset:13312
	ds_read_b128 v[208:211], v126 offset:14336
	ds_read_b128 v[212:215], v126 offset:15360
	s_waitcnt lgkmcnt(0)
	v_mfma_f32_16x16x32_bf16 v[92:95], v[200:203], v[134:137], v[92:95]
	v_mfma_f32_16x16x32_bf16 v[88:91], v[204:207], v[134:137], v[88:91]
	v_mfma_f32_16x16x32_bf16 v[84:87], v[208:211], v[134:137], v[84:87]
	v_mfma_f32_16x16x32_bf16 v[80:83], v[212:215], v[134:137], v[80:83]
	v_mfma_f32_16x16x32_bf16 v[76:79], v[200:203], v[138:141], v[76:79]
	v_mfma_f32_16x16x32_bf16 v[72:75], v[204:207], v[138:141], v[72:75]
	v_mfma_f32_16x16x32_bf16 v[68:71], v[208:211], v[138:141], v[68:71]
	v_mfma_f32_16x16x32_bf16 v[64:67], v[212:215], v[138:141], v[64:67]
	v_mfma_f32_16x16x32_bf16 v[60:63], v[200:203], v[154:157], v[60:63]
	v_mfma_f32_16x16x32_bf16 v[56:59], v[204:207], v[154:157], v[56:59]
	v_mfma_f32_16x16x32_bf16 v[52:55], v[208:211], v[154:157], v[52:55]
	v_mfma_f32_16x16x32_bf16 v[48:51], v[212:215], v[154:157], v[48:51]
	v_mfma_f32_16x16x32_bf16 v[44:47], v[200:203], v[158:161], v[44:47]
	v_mfma_f32_16x16x32_bf16 v[40:43], v[204:207], v[158:161], v[40:43]
	v_mfma_f32_16x16x32_bf16 v[36:39], v[208:211], v[158:161], v[36:39]
	v_mfma_f32_16x16x32_bf16 v[32:35], v[212:215], v[158:161], v[32:35]
	v_mfma_f32_16x16x32_bf16 v[28:31], v[200:203], v[162:165], v[28:31]
	v_mfma_f32_16x16x32_bf16 v[24:27], v[204:207], v[162:165], v[24:27]
	v_mfma_f32_16x16x32_bf16 v[20:23], v[208:211], v[162:165], v[20:23]
	v_mfma_f32_16x16x32_bf16 v[16:19], v[212:215], v[162:165], v[16:19]
	v_mfma_f32_16x16x32_bf16 v[8:11], v[200:203], v[166:169], v[8:11]
	v_mfma_f32_16x16x32_bf16 v[4:7], v[204:207], v[166:169], v[4:7]
	v_mfma_f32_16x16x32_bf16 v[12:15], v[208:211], v[166:169], v[12:15]
	v_mfma_f32_16x16x32_bf16 v[0:3], v[212:215], v[166:169], v[0:3]
	s_cbranch_scc0 .LBB0_128
	v_add_u32_e32 v170, v147, v128
	v_add_u32_e32 v172, v149, v148
	s_waitcnt vmcnt(5)
	s_barrier
	ds_read_b128 v[116:119], v170
	ds_read_b128 v[120:123], v170 offset:1024
	ds_read_b128 v[124:127], v170 offset:2048
	ds_read_b128 v[134:137], v170 offset:3072
	ds_read_b128 v[138:141], v170 offset:4096
	ds_read_b128 v[154:157], v170 offset:5120
	ds_read_b128 v[158:161], v172 offset:12288
	ds_read_b128 v[162:165], v172 offset:13312
	ds_read_b128 v[166:169], v172 offset:14336
	ds_read_b128 v[200:203], v172 offset:15360
	s_waitcnt lgkmcnt(0)
	v_mfma_f32_16x16x32_bf16 v[92:95], v[158:161], v[116:119], v[92:95]
	s_waitcnt vmcnt(0)
	s_barrier
	v_readlane_b32 s12, v243, 5
	v_mfma_f32_16x16x32_bf16 v[88:91], v[162:165], v[116:119], v[88:91]
	v_readlane_b32 s18, v243, 11
	v_readlane_b32 s19, v243, 12
	v_readlane_b32 s13, v243, 6
	v_mfma_f32_16x16x32_bf16 v[84:87], v[166:169], v[116:119], v[84:87]
	v_readlane_b32 s14, v243, 7
	v_readlane_b32 s15, v243, 8
	v_readlane_b32 s16, v243, 9
	v_mfma_f32_16x16x32_bf16 v[80:83], v[200:203], v[116:119], v[80:83]
	v_readlane_b32 s17, v243, 10
	v_readlane_b32 s20, v243, 13
	v_readlane_b32 s21, v243, 14
	v_mfma_f32_16x16x32_bf16 v[76:79], v[158:161], v[120:123], v[76:79]
	v_readlane_b32 s22, v243, 15
	v_readlane_b32 s23, v243, 16
	v_readlane_b32 s24, v243, 17
	v_mfma_f32_16x16x32_bf16 v[72:75], v[162:165], v[120:123], v[72:75]
	v_readlane_b32 s25, v243, 18
	v_readlane_b32 s26, v243, 19
	v_readlane_b32 s27, v243, 20
	v_mfma_f32_16x16x32_bf16 v[68:71], v[166:169], v[120:123], v[68:71]
	s_mov_b64 s[10:11], 0x2000
	s_mov_b32 s6, 0x3fd744fd
	s_add_i32 s9, s9, s51
	v_mfma_f32_16x16x32_bf16 v[64:67], v[200:203], v[120:123], v[64:67]
	s_cmpk_gt_i32 s9, 0xff
	v_mfma_f32_16x16x32_bf16 v[60:63], v[158:161], v[124:127], v[60:63]
	v_mfma_f32_16x16x32_bf16 v[56:59], v[162:165], v[124:127], v[56:59]
	v_mfma_f32_16x16x32_bf16 v[52:55], v[166:169], v[124:127], v[52:55]
	v_mfma_f32_16x16x32_bf16 v[48:51], v[200:203], v[124:127], v[48:51]
	v_mfma_f32_16x16x32_bf16 v[44:47], v[158:161], v[134:137], v[44:47]
	v_mfma_f32_16x16x32_bf16 v[40:43], v[162:165], v[134:137], v[40:43]
	v_mfma_f32_16x16x32_bf16 v[36:39], v[166:169], v[134:137], v[36:39]
	v_mfma_f32_16x16x32_bf16 v[32:35], v[200:203], v[134:137], v[32:35]
	v_mfma_f32_16x16x32_bf16 v[28:31], v[158:161], v[138:141], v[28:31]
	v_mfma_f32_16x16x32_bf16 v[24:27], v[162:165], v[138:141], v[24:27]
	v_mfma_f32_16x16x32_bf16 v[20:23], v[166:169], v[138:141], v[20:23]
	v_mfma_f32_16x16x32_bf16 v[16:19], v[200:203], v[138:141], v[16:19]
	v_mfma_f32_16x16x32_bf16 v[8:11], v[158:161], v[154:157], v[8:11]
	v_mfma_f32_16x16x32_bf16 v[4:7], v[162:165], v[154:157], v[4:7]
	v_mfma_f32_16x16x32_bf16 v[116:119], v[166:169], v[154:157], v[12:15]
	v_mfma_f32_16x16x32_bf16 v[0:3], v[200:203], v[154:157], v[0:3]
	s_nop 1
	ds_read_b128 v[12:15], v170 offset:20480
	ds_read_b128 v[120:123], v170 offset:21504
	ds_read_b128 v[124:127], v170 offset:22528
	ds_read_b128 v[134:137], v170 offset:23552
	ds_read_b128 v[138:141], v170 offset:24576
	ds_read_b128 v[154:157], v170 offset:25600
	ds_read_b128 v[158:161], v172 offset:32768
	ds_read_b128 v[162:165], v172 offset:33792
	ds_read_b128 v[166:169], v172 offset:34816
	ds_read_b128 v[200:203], v172 offset:35840
	s_waitcnt lgkmcnt(0)
	v_mfma_f32_16x16x32_bf16 v[76:79], v[158:161], v[120:123], v[76:79]
	v_mfma_f32_16x16x32_bf16 v[72:75], v[162:165], v[120:123], v[72:75]
	v_mfma_f32_16x16x32_bf16 v[68:71], v[166:169], v[120:123], v[68:71]
	v_mfma_f32_16x16x32_bf16 v[64:67], v[200:203], v[120:123], v[64:67]
	v_mfma_f32_16x16x32_bf16 v[204:207], v[158:161], v[12:15], v[92:95]
	v_mfma_f32_16x16x32_bf16 v[88:91], v[162:165], v[12:15], v[88:91]
	v_mfma_f32_16x16x32_bf16 v[84:87], v[166:169], v[12:15], v[84:87]
	v_mfma_f32_16x16x32_bf16 v[80:83], v[200:203], v[12:15], v[80:83]
	v_mfma_f32_16x16x32_bf16 v[12:15], v[158:161], v[154:157], v[8:11]
	v_mfma_f32_16x16x32_bf16 v[8:11], v[162:165], v[154:157], v[4:7]
	v_mfma_f32_16x16x32_bf16 v[4:7], v[166:169], v[154:157], v[116:119]
	v_mfma_f32_16x16x32_bf16 v[28:31], v[158:161], v[138:141], v[28:31]
	v_mfma_f32_16x16x32_bf16 v[24:27], v[162:165], v[138:141], v[24:27]
	v_mfma_f32_16x16x32_bf16 v[20:23], v[166:169], v[138:141], v[20:23]
	v_mfma_f32_16x16x32_bf16 v[16:19], v[200:203], v[138:141], v[16:19]
	v_mfma_f32_16x16x32_bf16 v[60:63], v[158:161], v[124:127], v[60:63]
	v_mfma_f32_16x16x32_bf16 v[56:59], v[162:165], v[124:127], v[56:59]
	v_mfma_f32_16x16x32_bf16 v[52:55], v[166:169], v[124:127], v[52:55]
	v_mfma_f32_16x16x32_bf16 v[48:51], v[200:203], v[124:127], v[48:51]
	v_mfma_f32_16x16x32_bf16 v[44:47], v[158:161], v[134:137], v[44:47]
	v_mfma_f32_16x16x32_bf16 v[40:43], v[162:165], v[134:137], v[40:43]
	v_mfma_f32_16x16x32_bf16 v[36:39], v[166:169], v[134:137], v[36:39]
	v_mfma_f32_16x16x32_bf16 v[32:35], v[200:203], v[134:137], v[32:35]
	v_mfma_f32_16x16x32_bf16 v[0:3], v[200:203], v[154:157], v[0:3]
	v_readlane_b32 s10, v241, 9
	s_cmp_eq_u32 s10, 7
	s_cbranch_scc0 .Lout_epi_ln
	v_readlane_b32 s10, v243, 21
	v_readlane_b32 s11, v243, 22
	v_readlane_b32 s12, v242, 29
	v_readlane_b32 s13, v242, 30
	v_readlane_b32 s14, v243, 11
	v_readlane_b32 s15, v243, 12
	s_mov_b32 s6, 0x3fd744fd
	v_add_u32_e32 v236, s0, v145
	v_or_b32_e32 v254, s4, v146
	v_mov_b32_e32 v255, 0
	v_or_b32_e32 v237, v236, v133
	v_lshlrev_b64 v[254:255], 2, v[254:255]
	s_nop 0
	v_lshl_add_u64 v[248:249], s[10:11], 0, v[254:255]
	v_lshl_add_u64 v[250:251], s[12:13], 0, v[254:255]
	v_lshl_add_u64 v[252:253], s[14:15], 0, v[254:255]
	s_mov_b64 s[10:11], 0x2000
	v_mov_b32_e32 v255, 0
	v_lshl_add_u64 v[252:253], v[252:253], 0, s[10:11]
	v_readlane_b32 s10, v243, 21
	v_readlane_b32 s11, v243, 22
	v_readlane_b32 s12, v243, 23
	v_readlane_b32 s13, v243, 24
	s_sub_u32 s12, s12, s10
	s_subb_u32 s13, s13, s11
	s_sub_u32 s12, s12, 0x1000000
	s_subb_u32 s13, s13, 0
	v_add_u32_e32 v254, 0, v237
	v_add_u32_e32 v236, 0xfffff000, v254
	v_cmp_lt_i32_e32 vcc, 0xfff, v254
	v_lshrrev_b32_e32 v236, 10, v236
	v_lshlrev_b32_e32 v254, 12, v254
	v_add_u32_e32 v236, 1, v236
	v_cndmask_b32_e32 v236, 0, v236, vcc
	v_lshl_add_u64 v[224:225], v[254:255], 0, v[248:249]
	v_lshl_add_u64 v[228:229], v[254:255], 0, v[250:251]
	v_add_u32_e32 v236, s8, v236
	v_mad_i64_i32 v[232:233], s[0:1], v236, s33, v[252:253]
	v_mov_b32_e32 v236, s12
	v_mov_b32_e32 v254, s13
	v_cndmask_b32_e32 v236, 0, v236, vcc
	v_cndmask_b32_e32 v254, 0, v254, vcc
	v_add_co_u32_e32 v224, vcc, v224, v236
	s_nop 0
	v_addc_co_u32_e32 v225, vcc, v225, v254, vcc
	v_add_u32_e32 v254, 16, v237
	v_add_u32_e32 v236, 0xfffff000, v254
	v_cmp_lt_i32_e32 vcc, 0xfff, v254
	v_lshrrev_b32_e32 v236, 10, v236
	v_lshlrev_b32_e32 v254, 12, v254
	v_add_u32_e32 v236, 1, v236
	v_cndmask_b32_e32 v236, 0, v236, vcc
	v_lshl_add_u64 v[226:227], v[254:255], 0, v[248:249]
	v_lshl_add_u64 v[230:231], v[254:255], 0, v[250:251]
	v_add_u32_e32 v236, s8, v236
	v_mad_i64_i32 v[234:235], s[0:1], v236, s33, v[252:253]
	v_mov_b32_e32 v236, s12
	v_mov_b32_e32 v254, s13
	v_cndmask_b32_e32 v236, 0, v236, vcc
	v_cndmask_b32_e32 v254, 0, v254, vcc
	v_add_co_u32_e32 v226, vcc, v226, v236
	s_nop 0
	v_addc_co_u32_e32 v227, vcc, v227, v254, vcc
	global_load_dwordx4 v[154:157], v[224:225], off
	global_load_dwordx4 v[116:119], v[232:233], off
	global_load_dwordx4 v[158:161], v[224:225], off offset:64
	global_load_dwordx4 v[120:123], v[232:233], off offset:64
	global_load_dwordx4 v[162:165], v[224:225], off offset:128
	global_load_dwordx4 v[124:127], v[232:233], off offset:128
	global_load_dwordx4 v[166:169], v[224:225], off offset:192
	global_load_dwordx4 v[134:137], v[232:233], off offset:192
	global_load_dwordx4 v[208:211], v[226:227], off
	global_load_dwordx4 v[138:141], v[234:235], off
	global_load_dwordx4 v[212:215], v[226:227], off offset:64
	global_load_dwordx4 v[200:203], v[234:235], off offset:64
	global_load_dwordx4 v[216:219], v[226:227], off offset:128
	global_load_dwordx4 v[92:95], v[234:235], off offset:128
	global_load_dwordx4 v[220:223], v[226:227], off offset:192
	global_load_dwordx4 v[244:247], v[234:235], off offset:192
	s_waitcnt vmcnt(0)
	v_pk_mul_f32 v[204:205], v[204:205], v[116:117]
	v_pk_mul_f32 v[206:207], v[206:207], v[118:119]
	v_pk_fma_f32 v[204:205], v[154:155], s[6:7], v[204:205] op_sel_hi:[1,0,1]
	v_pk_fma_f32 v[206:207], v[156:157], s[6:7], v[206:207] op_sel_hi:[1,0,1]
	global_store_dwordx4 v[228:229], v[204:207], off
	v_pk_mul_f32 v[88:89], v[88:89], v[120:121]
	v_pk_mul_f32 v[90:91], v[90:91], v[122:123]
	v_pk_fma_f32 v[88:89], v[158:159], s[6:7], v[88:89] op_sel_hi:[1,0,1]
	v_pk_fma_f32 v[90:91], v[160:161], s[6:7], v[90:91] op_sel_hi:[1,0,1]
	global_store_dwordx4 v[228:229], v[88:91], off offset:64
	v_pk_mul_f32 v[84:85], v[84:85], v[124:125]
	v_pk_mul_f32 v[86:87], v[86:87], v[126:127]
	v_pk_fma_f32 v[84:85], v[162:163], s[6:7], v[84:85] op_sel_hi:[1,0,1]
	v_pk_fma_f32 v[86:87], v[164:165], s[6:7], v[86:87] op_sel_hi:[1,0,1]
	global_store_dwordx4 v[228:229], v[84:87], off offset:128
	v_pk_mul_f32 v[80:81], v[80:81], v[134:135]
	v_pk_mul_f32 v[82:83], v[82:83], v[136:137]
	v_pk_fma_f32 v[80:81], v[166:167], s[6:7], v[80:81] op_sel_hi:[1,0,1]
	v_pk_fma_f32 v[82:83], v[168:169], s[6:7], v[82:83] op_sel_hi:[1,0,1]
	global_store_dwordx4 v[228:229], v[80:83], off offset:192
	v_pk_mul_f32 v[76:77], v[76:77], v[138:139]
	v_pk_mul_f32 v[78:79], v[78:79], v[140:141]
	v_pk_fma_f32 v[76:77], v[208:209], s[6:7], v[76:77] op_sel_hi:[1,0,1]
	v_pk_fma_f32 v[78:79], v[210:211], s[6:7], v[78:79] op_sel_hi:[1,0,1]
	global_store_dwordx4 v[230:231], v[76:79], off
	v_pk_mul_f32 v[72:73], v[72:73], v[200:201]
	v_pk_mul_f32 v[74:75], v[74:75], v[202:203]
	v_pk_fma_f32 v[72:73], v[212:213], s[6:7], v[72:73] op_sel_hi:[1,0,1]
	v_pk_fma_f32 v[74:75], v[214:215], s[6:7], v[74:75] op_sel_hi:[1,0,1]
	global_store_dwordx4 v[230:231], v[72:75], off offset:64
	v_pk_mul_f32 v[68:69], v[68:69], v[92:93]
	v_pk_mul_f32 v[70:71], v[70:71], v[94:95]
	v_pk_fma_f32 v[68:69], v[216:217], s[6:7], v[68:69] op_sel_hi:[1,0,1]
	v_pk_fma_f32 v[70:71], v[218:219], s[6:7], v[70:71] op_sel_hi:[1,0,1]
	global_store_dwordx4 v[230:231], v[68:71], off offset:128
	v_pk_mul_f32 v[64:65], v[64:65], v[244:245]
	v_pk_mul_f32 v[66:67], v[66:67], v[246:247]
	v_pk_fma_f32 v[64:65], v[220:221], s[6:7], v[64:65] op_sel_hi:[1,0,1]
	v_pk_fma_f32 v[66:67], v[222:223], s[6:7], v[66:67] op_sel_hi:[1,0,1]
	global_store_dwordx4 v[230:231], v[64:67], off offset:192
	v_add_u32_e32 v254, 32, v237
	v_add_u32_e32 v236, 0xfffff000, v254
	v_cmp_lt_i32_e32 vcc, 0xfff, v254
	v_lshrrev_b32_e32 v236, 10, v236
	v_lshlrev_b32_e32 v254, 12, v254
	v_add_u32_e32 v236, 1, v236
	v_cndmask_b32_e32 v236, 0, v236, vcc
	v_lshl_add_u64 v[224:225], v[254:255], 0, v[248:249]
	v_lshl_add_u64 v[228:229], v[254:255], 0, v[250:251]
	v_add_u32_e32 v236, s8, v236
	v_mad_i64_i32 v[232:233], s[0:1], v236, s33, v[252:253]
	v_mov_b32_e32 v236, s12
	v_mov_b32_e32 v254, s13
	v_cndmask_b32_e32 v236, 0, v236, vcc
	v_cndmask_b32_e32 v254, 0, v254, vcc
	v_add_co_u32_e32 v224, vcc, v224, v236
	s_nop 0
	v_addc_co_u32_e32 v225, vcc, v225, v254, vcc
	v_add_u32_e32 v254, 48, v237
	v_add_u32_e32 v236, 0xfffff000, v254
	v_cmp_lt_i32_e32 vcc, 0xfff, v254
	v_lshrrev_b32_e32 v236, 10, v236
	v_lshlrev_b32_e32 v254, 12, v254
	v_add_u32_e32 v236, 1, v236
	v_cndmask_b32_e32 v236, 0, v236, vcc
	v_lshl_add_u64 v[226:227], v[254:255], 0, v[248:249]
	v_lshl_add_u64 v[230:231], v[254:255], 0, v[250:251]
	v_add_u32_e32 v236, s8, v236
	v_mad_i64_i32 v[234:235], s[0:1], v236, s33, v[252:253]
	v_mov_b32_e32 v236, s12
	v_mov_b32_e32 v254, s13
	v_cndmask_b32_e32 v236, 0, v236, vcc
	v_cndmask_b32_e32 v254, 0, v254, vcc
	v_add_co_u32_e32 v226, vcc, v226, v236
	s_nop 0
	v_addc_co_u32_e32 v227, vcc, v227, v254, vcc
	global_load_dwordx4 v[154:157], v[224:225], off
	global_load_dwordx4 v[116:119], v[232:233], off
	global_load_dwordx4 v[158:161], v[224:225], off offset:64
	global_load_dwordx4 v[120:123], v[232:233], off offset:64
	global_load_dwordx4 v[162:165], v[224:225], off offset:128
	global_load_dwordx4 v[124:127], v[232:233], off offset:128
	global_load_dwordx4 v[166:169], v[224:225], off offset:192
	global_load_dwordx4 v[134:137], v[232:233], off offset:192
	global_load_dwordx4 v[208:211], v[226:227], off
	global_load_dwordx4 v[138:141], v[234:235], off
	global_load_dwordx4 v[212:215], v[226:227], off offset:64
	global_load_dwordx4 v[200:203], v[234:235], off offset:64
	global_load_dwordx4 v[216:219], v[226:227], off offset:128
	global_load_dwordx4 v[92:95], v[234:235], off offset:128
	global_load_dwordx4 v[220:223], v[226:227], off offset:192
	global_load_dwordx4 v[244:247], v[234:235], off offset:192
	s_waitcnt vmcnt(0)
	v_pk_mul_f32 v[60:61], v[60:61], v[116:117]
	v_pk_mul_f32 v[62:63], v[62:63], v[118:119]
	v_pk_fma_f32 v[60:61], v[154:155], s[6:7], v[60:61] op_sel_hi:[1,0,1]
	v_pk_fma_f32 v[62:63], v[156:157], s[6:7], v[62:63] op_sel_hi:[1,0,1]
	global_store_dwordx4 v[228:229], v[60:63], off
	v_pk_mul_f32 v[56:57], v[56:57], v[120:121]
	v_pk_mul_f32 v[58:59], v[58:59], v[122:123]
	v_pk_fma_f32 v[56:57], v[158:159], s[6:7], v[56:57] op_sel_hi:[1,0,1]
	v_pk_fma_f32 v[58:59], v[160:161], s[6:7], v[58:59] op_sel_hi:[1,0,1]
	global_store_dwordx4 v[228:229], v[56:59], off offset:64
	v_pk_mul_f32 v[52:53], v[52:53], v[124:125]
	v_pk_mul_f32 v[54:55], v[54:55], v[126:127]
	v_pk_fma_f32 v[52:53], v[162:163], s[6:7], v[52:53] op_sel_hi:[1,0,1]
	v_pk_fma_f32 v[54:55], v[164:165], s[6:7], v[54:55] op_sel_hi:[1,0,1]
	global_store_dwordx4 v[228:229], v[52:55], off offset:128
	v_pk_mul_f32 v[48:49], v[48:49], v[134:135]
	v_pk_mul_f32 v[50:51], v[50:51], v[136:137]
	v_pk_fma_f32 v[48:49], v[166:167], s[6:7], v[48:49] op_sel_hi:[1,0,1]
	v_pk_fma_f32 v[50:51], v[168:169], s[6:7], v[50:51] op_sel_hi:[1,0,1]
	global_store_dwordx4 v[228:229], v[48:51], off offset:192
	v_pk_mul_f32 v[44:45], v[44:45], v[138:139]
	v_pk_mul_f32 v[46:47], v[46:47], v[140:141]
	v_pk_fma_f32 v[44:45], v[208:209], s[6:7], v[44:45] op_sel_hi:[1,0,1]
	v_pk_fma_f32 v[46:47], v[210:211], s[6:7], v[46:47] op_sel_hi:[1,0,1]
	global_store_dwordx4 v[230:231], v[44:47], off
	v_pk_mul_f32 v[40:41], v[40:41], v[200:201]
	v_pk_mul_f32 v[42:43], v[42:43], v[202:203]
	v_pk_fma_f32 v[40:41], v[212:213], s[6:7], v[40:41] op_sel_hi:[1,0,1]
	v_pk_fma_f32 v[42:43], v[214:215], s[6:7], v[42:43] op_sel_hi:[1,0,1]
	global_store_dwordx4 v[230:231], v[40:43], off offset:64
	v_pk_mul_f32 v[36:37], v[36:37], v[92:93]
	v_pk_mul_f32 v[38:39], v[38:39], v[94:95]
	v_pk_fma_f32 v[36:37], v[216:217], s[6:7], v[36:37] op_sel_hi:[1,0,1]
	v_pk_fma_f32 v[38:39], v[218:219], s[6:7], v[38:39] op_sel_hi:[1,0,1]
	global_store_dwordx4 v[230:231], v[36:39], off offset:128
	v_pk_mul_f32 v[32:33], v[32:33], v[244:245]
	v_pk_mul_f32 v[34:35], v[34:35], v[246:247]
	v_pk_fma_f32 v[32:33], v[220:221], s[6:7], v[32:33] op_sel_hi:[1,0,1]
	v_pk_fma_f32 v[34:35], v[222:223], s[6:7], v[34:35] op_sel_hi:[1,0,1]
	global_store_dwordx4 v[230:231], v[32:35], off offset:192
	v_add_u32_e32 v254, 64, v237
	v_add_u32_e32 v236, 0xfffff000, v254
	v_cmp_lt_i32_e32 vcc, 0xfff, v254
	v_lshrrev_b32_e32 v236, 10, v236
	v_lshlrev_b32_e32 v254, 12, v254
	v_add_u32_e32 v236, 1, v236
	v_cndmask_b32_e32 v236, 0, v236, vcc
	v_lshl_add_u64 v[224:225], v[254:255], 0, v[248:249]
	v_lshl_add_u64 v[228:229], v[254:255], 0, v[250:251]
	v_add_u32_e32 v236, s8, v236
	v_mad_i64_i32 v[232:233], s[0:1], v236, s33, v[252:253]
	v_mov_b32_e32 v236, s12
	v_mov_b32_e32 v254, s13
	v_cndmask_b32_e32 v236, 0, v236, vcc
	v_cndmask_b32_e32 v254, 0, v254, vcc
	v_add_co_u32_e32 v224, vcc, v224, v236
	s_nop 0
	v_addc_co_u32_e32 v225, vcc, v225, v254, vcc
	v_add_u32_e32 v254, 80, v237
	v_add_u32_e32 v236, 0xfffff000, v254
	v_cmp_lt_i32_e32 vcc, 0xfff, v254
	v_lshrrev_b32_e32 v236, 10, v236
	v_lshlrev_b32_e32 v254, 12, v254
	v_add_u32_e32 v236, 1, v236
	v_cndmask_b32_e32 v236, 0, v236, vcc
	v_lshl_add_u64 v[226:227], v[254:255], 0, v[248:249]
	v_lshl_add_u64 v[230:231], v[254:255], 0, v[250:251]
	v_add_u32_e32 v236, s8, v236
	v_mad_i64_i32 v[234:235], s[0:1], v236, s33, v[252:253]
	v_mov_b32_e32 v236, s12
	v_mov_b32_e32 v254, s13
	v_cndmask_b32_e32 v236, 0, v236, vcc
	v_cndmask_b32_e32 v254, 0, v254, vcc
	v_add_co_u32_e32 v226, vcc, v226, v236
	s_nop 0
	v_addc_co_u32_e32 v227, vcc, v227, v254, vcc
	global_load_dwordx4 v[154:157], v[224:225], off
	global_load_dwordx4 v[116:119], v[232:233], off
	global_load_dwordx4 v[158:161], v[224:225], off offset:64
	global_load_dwordx4 v[120:123], v[232:233], off offset:64
	global_load_dwordx4 v[162:165], v[224:225], off offset:128
	global_load_dwordx4 v[124:127], v[232:233], off offset:128
	global_load_dwordx4 v[166:169], v[224:225], off offset:192
	global_load_dwordx4 v[134:137], v[232:233], off offset:192
	global_load_dwordx4 v[208:211], v[226:227], off
	global_load_dwordx4 v[138:141], v[234:235], off
	global_load_dwordx4 v[212:215], v[226:227], off offset:64
	global_load_dwordx4 v[200:203], v[234:235], off offset:64
	global_load_dwordx4 v[216:219], v[226:227], off offset:128
	global_load_dwordx4 v[92:95], v[234:235], off offset:128
	global_load_dwordx4 v[220:223], v[226:227], off offset:192
	global_load_dwordx4 v[244:247], v[234:235], off offset:192
	s_waitcnt vmcnt(0)
	v_pk_mul_f32 v[28:29], v[28:29], v[116:117]
	v_pk_mul_f32 v[30:31], v[30:31], v[118:119]
	v_pk_fma_f32 v[28:29], v[154:155], s[6:7], v[28:29] op_sel_hi:[1,0,1]
	v_pk_fma_f32 v[30:31], v[156:157], s[6:7], v[30:31] op_sel_hi:[1,0,1]
	global_store_dwordx4 v[228:229], v[28:31], off
	v_pk_mul_f32 v[24:25], v[24:25], v[120:121]
	v_pk_mul_f32 v[26:27], v[26:27], v[122:123]
	v_pk_fma_f32 v[24:25], v[158:159], s[6:7], v[24:25] op_sel_hi:[1,0,1]
	v_pk_fma_f32 v[26:27], v[160:161], s[6:7], v[26:27] op_sel_hi:[1,0,1]
	global_store_dwordx4 v[228:229], v[24:27], off offset:64
	v_pk_mul_f32 v[20:21], v[20:21], v[124:125]
	v_pk_mul_f32 v[22:23], v[22:23], v[126:127]
	v_pk_fma_f32 v[20:21], v[162:163], s[6:7], v[20:21] op_sel_hi:[1,0,1]
	v_pk_fma_f32 v[22:23], v[164:165], s[6:7], v[22:23] op_sel_hi:[1,0,1]
	global_store_dwordx4 v[228:229], v[20:23], off offset:128
	v_pk_mul_f32 v[16:17], v[16:17], v[134:135]
	v_pk_mul_f32 v[18:19], v[18:19], v[136:137]
	v_pk_fma_f32 v[16:17], v[166:167], s[6:7], v[16:17] op_sel_hi:[1,0,1]
	v_pk_fma_f32 v[18:19], v[168:169], s[6:7], v[18:19] op_sel_hi:[1,0,1]
	global_store_dwordx4 v[228:229], v[16:19], off offset:192
	v_pk_mul_f32 v[12:13], v[12:13], v[138:139]
	v_pk_mul_f32 v[14:15], v[14:15], v[140:141]
	v_pk_fma_f32 v[12:13], v[208:209], s[6:7], v[12:13] op_sel_hi:[1,0,1]
	v_pk_fma_f32 v[14:15], v[210:211], s[6:7], v[14:15] op_sel_hi:[1,0,1]
	global_store_dwordx4 v[230:231], v[12:15], off
	v_pk_mul_f32 v[8:9], v[8:9], v[200:201]
	v_pk_mul_f32 v[10:11], v[10:11], v[202:203]
	v_pk_fma_f32 v[8:9], v[212:213], s[6:7], v[8:9] op_sel_hi:[1,0,1]
	v_pk_fma_f32 v[10:11], v[214:215], s[6:7], v[10:11] op_sel_hi:[1,0,1]
	global_store_dwordx4 v[230:231], v[8:11], off offset:64
	v_pk_mul_f32 v[4:5], v[4:5], v[92:93]
	v_pk_mul_f32 v[6:7], v[6:7], v[94:95]
	v_pk_fma_f32 v[4:5], v[216:217], s[6:7], v[4:5] op_sel_hi:[1,0,1]
	v_pk_fma_f32 v[6:7], v[218:219], s[6:7], v[6:7] op_sel_hi:[1,0,1]
	global_store_dwordx4 v[230:231], v[4:7], off offset:128
	v_pk_mul_f32 v[0:1], v[0:1], v[244:245]
	v_pk_mul_f32 v[2:3], v[2:3], v[246:247]
	v_pk_fma_f32 v[0:1], v[220:221], s[6:7], v[0:1] op_sel_hi:[1,0,1]
	v_pk_fma_f32 v[2:3], v[222:223], s[6:7], v[2:3] op_sel_hi:[1,0,1]
	global_store_dwordx4 v[230:231], v[0:3], off offset:192
	s_branch .Lout_epi_done
